# GEMM K-loops without per-segment s_setprio flips plus one static s_setprio 1 for the leading wave half (waves 0-3) for the whole GEMM phase
# speedup vs baseline: 1.0064x; 1.0037x over previous
; #define PG8_STAGE(bufoff, gbase, voff) do { _Pragma("unroll") for (int _i = 0; _i < 2; ++_i) \
;         __builtin_amdgcn_global_load_lds((const unsigned*)((const char*)(gbase) + (voff)[_i]), (PG8_LAS unsigned*)(lds + (bufoff) + ldsw + _i * 8192), 16, 0, 0); } while (0)
; #define PG8_BAR __builtin_amdgcn_s_barrier()
; template <class Epi, class Sched, bool ALIGN_EPI = false, bool SP2 = false>
; __device__ __forceinline__ void gemm_phase(PG8_LAS unsigned char* lds, const Gemm g, const Sched& S, const Epi& E) {
;     ...
;     for (int i = 0; i < 2; ++i) { int R, C; stage_rc(tid * 16 + i * 8192, R, C); const int Rb = Epi::PERM ? (64 * (R >> 5) + perm32(R & 31)) : R;
;         voffA[i] = (unsigned)(R * K + C) * 2u; voffB[i] = (unsigned)(Rb * K + C) * 2u; }
;     ...
;         PG8_STAGE(PG8_SB(0, 0), cB, voffB); PG8_STAGE(PG8_SB(0, 1), cB + hstepB, voffB); PG8_STAGE(PG8_SA(0, 0), cA, voffA); PG8_STAGE(PG8_SA(0, 1), cA + hstep, voffA);
;         if (wr == 1) PG8_BAR;
.LBB0_163:
	s_or_b64 exec, exec, s[26:27]
	s_waitcnt vmcnt(0)
	v_bfe_i32 v3, v26, 27, 1
	v_lshlrev_b32_e32 v1, 4, v26
	v_lshrrev_b32_e32 v3, 22, v3
	v_ashrrev_i32_e32 v2, 31, v26
	v_add_u32_e32 v3, v1, v3
	v_lshrrev_b32_e32 v2, 26, v2
	v_and_b32_e32 v3, 0xfffffc00, v3
	v_add_u32_e32 v2, v26, v2
	v_sub_u32_e32 v3, v1, v3
	v_ashrrev_i32_e32 v2, 6, v2
	v_lshrrev_b32_e32 v4, 4, v3
	v_bitop3_b32 v4, v4, v3, 32 bitop3:0x6c
	v_lshlrev_b32_e32 v3, 3, v2
	v_and_b32_e32 v5, -16, v3
	v_ashrrev_i32_e32 v3, 31, v4
	v_lshrrev_b32_e32 v3, 26, v3
	v_add_u32_e32 v6, v4, v3
	v_ashrrev_i32_e32 v3, 6, v6
	v_and_b32_e32 v6, 0xc0, v6
	v_sub_u32_e32 v4, v4, v6
	v_lshlrev_b32_e32 v7, 5, v2
	v_ashrrev_i16_sdwa v4, v225, sext(v4) dst_sel:DWORD dst_unused:UNUSED_PAD src0_sel:DWORD src1_sel:BYTE_0
	v_and_b32_e32 v7, 32, v7
	v_bfe_i32 v4, v4, 0, 16
	v_add_u32_e32 v5, v3, v5
	v_add_lshl_u32 v7, v7, v4, 1
	v_add_u32_e32 v1, 0x2000, v1
	v_lshlrev_b32_e32 v6, 1, v5
	v_lshrrev_b32_e32 v8, 2, v5
	v_lshl_add_u32 v130, v5, 12, v7
	v_ashrrev_i32_e32 v5, 31, v1
	v_lshrrev_b32_e32 v5, 22, v5
	v_and_b32_e32 v8, 4, v8
	v_and_b32_e32 v9, 3, v3
	v_and_b32_e32 v6, 0xfffd8, v6
	v_add_u32_e32 v5, v1, v5
	v_or3_b32 v6, v9, v8, v6
	v_ashrrev_i32_e32 v5, 10, v5
	v_lshl_add_u32 v132, v6, 12, v7
	v_mul_i32_i24_e32 v6, 0x400, v5
	v_sub_u32_e32 v1, v1, v6
	v_lshrrev_b32_e32 v6, 4, v1
	v_bitop3_b32 v1, v6, v1, 32 bitop3:0x6c
	v_lshlrev_b32_e32 v6, 3, v5
	v_and_b32_e32 v7, -16, v6
	v_ashrrev_i32_e32 v6, 31, v1
	v_lshrrev_b32_e32 v6, 26, v6
	v_add_u32_e32 v8, v1, v6
	v_ashrrev_i32_e32 v6, 6, v8
	v_add_u32_e32 v9, v6, v7
	v_lshlrev_b32_e32 v7, 5, v5
	v_and_b32_e32 v10, 32, v7
	v_and_b32_e32 v7, 0xc0, v8
	v_sub_u32_e32 v1, v1, v7
	s_ashr_i32 s4, s36, 6
	v_ashrrev_i16_sdwa v1, v225, sext(v1) dst_sel:DWORD dst_unused:UNUSED_PAD src0_sel:DWORD src1_sel:BYTE_0
	v_bfe_i32 v7, v1, 0, 16
	v_lshlrev_b32_e32 v1, 1, v9
	v_lshrrev_b32_e32 v8, 2, v9
	s_lshl_b32 s0, s4, 10
	v_and_b32_e32 v8, 4, v8
	v_and_b32_e32 v11, 3, v6
	v_and_b32_e32 v1, 0xfffd8, v1
	s_add_i32 s1, s0, 0
	v_readlane_b32 s6, v254, 24
	v_or3_b32 v1, v11, v8, v1
	v_add_lshl_u32 v8, v10, v7, 1
	s_add_i32 m0, s1, 0x10000
	v_readlane_b32 s7, v254, 25
	v_lshl_add_u32 v136, v1, 12, v8
	s_add_i32 s25, s1, 0x2000
	v_lshl_add_u32 v134, v9, 12, v8
	s_add_i32 s42, s1, 0x4000
	s_add_i32 s51, s1, 0x6000
	global_load_lds_dwordx4 v132, s[6:7]
	s_add_i32 m0, s1, 0x12000
	s_ashr_i32 s5, s36, 8
	global_load_lds_dwordx4 v136, s[6:7]
	v_readlane_b32 s6, v254, 18
	s_add_i32 m0, s1, 0x14000
	v_readlane_b32 s7, v254, 19
	s_nop 4
	global_load_lds_dwordx4 v132, s[6:7]
	s_add_i32 m0, s1, 0x16000
	s_cmp_eq_u32 s5, 1
	global_load_lds_dwordx4 v136, s[6:7]
	v_readlane_b32 s6, v254, 20
	s_mov_b32 m0, s1
	v_readlane_b32 s7, v254, 21
	s_cselect_b64 s[26:27], -1, 0
	s_cmp_lg_u32 s5, 1
	s_nop 2
	global_load_lds_dwordx4 v130, s[6:7]
	s_mov_b32 m0, s25
	s_nop 0
	global_load_lds_dwordx4 v134, s[6:7]
	v_readlane_b32 s6, v254, 22
	s_mov_b32 m0, s42
	v_readlane_b32 s7, v254, 23
	s_nop 4
	global_load_lds_dwordx4 v130, s[6:7]
	s_mov_b32 m0, s51
	s_nop 0
	global_load_lds_dwordx4 v134, s[6:7]
	s_setprio 1
	s_cbranch_scc1 .LBB0_165
	s_barrier
	s_setprio 0

; #define PG8_STAGE(bufoff, gbase, voff) do { _Pragma("unroll") for (int _i = 0; _i < 2; ++_i) \
;         __builtin_amdgcn_global_load_lds((const unsigned*)((const char*)(gbase) + (voff)[_i]), (PG8_LAS unsigned*)(lds + (bufoff) + ldsw + _i * 8192), 16, 0, 0); } while (0)
; #define PG8_BAR __builtin_amdgcn_s_barrier()
; template <class Epi, class Sched, bool ALIGN_EPI = false, bool SP2 = false>
; __device__ __forceinline__ void gemm_phase(PG8_LAS unsigned char* lds, const Gemm g, const Sched& S, const Epi& E) {
;     ...
;     for (int i = 0; i < 2; ++i) { int R, C; stage_rc(tid * 16 + i * 8192, R, C); const int Rb = Epi::PERM ? (64 * (R >> 5) + perm32(R & 31)) : R;
;         voffA[i] = (unsigned)(R * K + C) * 2u; voffB[i] = (unsigned)(Rb * K + C) * 2u; }
;     ...
;         PG8_STAGE(PG8_SB(0, 0), cB, voffB); PG8_STAGE(PG8_SB(0, 1), cB + hstepB, voffB); PG8_STAGE(PG8_SA(0, 0), cA, voffA); PG8_STAGE(PG8_SA(0, 1), cA + hstep, voffA);
;         if (wr == 1) PG8_BAR;
.LBB0_778:
	s_andn2_b64 vcc, exec, s[26:27]
	s_cbranch_vccnz .LBB0_849
	v_readlane_b32 s0, v252, 55
	s_waitcnt vmcnt(0) lgkmcnt(0)
	v_mov_b32_e32 v3, v0
	v_readlane_b32 s1, v252, 56
	s_waitcnt lgkmcnt(0)
	s_barrier
	s_andn2_b64 vcc, exec, s[0:1]
	v_readfirstlane_b32 s0, v3
	s_cbranch_vccnz .LBB0_795
	v_lshlrev_b32_e32 v1, 4, v3
	v_add_u32_e32 v4, 0x2000, v1
	v_ashrrev_i32_e32 v2, 31, v4
	v_lshrrev_b32_e32 v2, 22, v2
	v_add_u32_e32 v2, v4, v2
	v_ashrrev_i32_e32 v2, 10, v2
	v_mul_i32_i24_e32 v5, 0x400, v2
	v_sub_u32_e32 v4, v4, v5
	v_lshrrev_b32_e32 v5, 4, v4
	v_bitop3_b32 v5, v5, v4, 32 bitop3:0x6c
	v_ashrrev_i32_e32 v4, 31, v5
	v_lshrrev_b32_e32 v4, 26, v4
	v_add_u32_e32 v6, v5, v4
	v_lshlrev_b32_e32 v8, 3, v2
	v_ashrrev_i32_e32 v4, 6, v6
	v_and_b32_e32 v8, -16, v8
	v_add_u32_e32 v8, v4, v8
	v_lshrrev_b32_e32 v9, 2, v8
	v_lshlrev_b32_e32 v10, 1, v8
	v_and_b32_e32 v6, 0xc0, v6
	v_and_b32_e32 v7, 3, v4
	v_and_b32_e32 v9, 4, v9
	v_and_b32_e32 v10, 0x3fffd8, v10
	v_sub_u32_e32 v5, v5, v6
	v_or3_b32 v7, v7, v9, v10
	v_lshlrev_b32_e32 v9, 5, v2
	v_ashrrev_i16_sdwa v5, v225, sext(v5) dst_sel:DWORD dst_unused:UNUSED_PAD src0_sel:DWORD src1_sel:BYTE_0
	v_and_b32_e32 v9, 32, v9
	v_bfe_i32 v5, v5, 0, 16
	v_add_lshl_u32 v6, v9, v5, 1
	v_lshl_add_u32 v174, v7, 10, v6
	v_lshl_add_u32 v176, v8, 10, v6
	v_bfe_i32 v6, v3, 27, 1
	v_lshrrev_b32_e32 v6, 22, v6
	v_add_u32_e32 v6, v1, v6
	v_and_b32_e32 v6, 0xfffffc00, v6
	v_sub_u32_e32 v1, v1, v6
	v_lshrrev_b32_e32 v6, 4, v1
	v_ashrrev_i32_e32 v7, 31, v3
	v_bitop3_b32 v1, v6, v1, 32 bitop3:0x6c
	v_lshrrev_b32_e32 v7, 26, v7
	v_ashrrev_i32_e32 v6, 31, v1
	v_add_u32_e32 v7, v3, v7
	v_lshrrev_b32_e32 v6, 26, v6
	v_ashrrev_i32_e32 v7, 6, v7
	v_add_u32_e32 v8, v1, v6
	v_lshlrev_b32_e32 v10, 3, v7
	v_ashrrev_i32_e32 v6, 6, v8
	v_and_b32_e32 v10, -16, v10
	v_add_u32_e32 v10, v6, v10
	v_lshrrev_b32_e32 v11, 2, v10
	v_lshlrev_b32_e32 v12, 1, v10
	v_and_b32_e32 v8, 0xc0, v8
	v_and_b32_e32 v9, 3, v6
	v_and_b32_e32 v11, 4, v11
	v_and_b32_e32 v12, 0x3fffd8, v12
	v_sub_u32_e32 v1, v1, v8
	s_ashr_i32 s1, s0, 6
	v_or3_b32 v9, v9, v11, v12
	v_lshlrev_b32_e32 v11, 5, v7
	v_ashrrev_i16_sdwa v1, v225, sext(v1) dst_sel:DWORD dst_unused:UNUSED_PAD src0_sel:DWORD src1_sel:BYTE_0
	s_lshl_b32 s25, s1, 10
	v_and_b32_e32 v11, 32, v11
	v_bfe_i32 v8, v1, 0, 16
	v_add_lshl_u32 v1, v11, v8, 1
	s_add_i32 s66, s25, 0
	v_readlane_b32 s4, v253, 50
	v_lshl_add_u32 v190, v9, 10, v1
	s_add_i32 m0, s66, 0x10000
	v_readlane_b32 s5, v253, 51
	v_lshl_add_u32 v178, v10, 10, v1
	s_add_i32 s67, s66, 0x2000
	s_add_i32 s80, s66, 0x4000
	s_add_i32 s81, s66, 0x6000
	s_nop 0
	global_load_lds_dwordx4 v190, s[4:5]
	s_add_i32 m0, s66, 0x12000
	s_nop 0
	global_load_lds_dwordx4 v174, s[4:5]
	v_readlane_b32 s4, v253, 44
	s_add_i32 m0, s66, 0x14000
	v_readlane_b32 s5, v253, 45
	s_nop 4
	global_load_lds_dwordx4 v190, s[4:5]
	s_add_i32 m0, s66, 0x16000
	s_nop 0
	global_load_lds_dwordx4 v174, s[4:5]
	v_readlane_b32 s4, v253, 46
	s_mov_b32 m0, s66
	v_readlane_b32 s5, v253, 47
	s_nop 4
	global_load_lds_dwordx4 v178, s[4:5]
	s_mov_b32 m0, s67
	s_nop 0
	global_load_lds_dwordx4 v176, s[4:5]
	v_readlane_b32 s4, v253, 48
	s_mov_b32 m0, s80
	v_readlane_b32 s5, v253, 49
	s_nop 4
	global_load_lds_dwordx4 v178, s[4:5]
	s_mov_b32 m0, s81
	s_nop 0
	global_load_lds_dwordx4 v176, s[4:5]
	s_ashr_i32 s4, s0, 8
	s_cmp_eq_u32 s4, 1
	s_cselect_b64 s[26:27], -1, 0
	s_cmp_lg_u32 s4, 1
	s_setprio 1
	s_cbranch_scc1 .LBB0_782
	s_barrier
	s_setprio 0

; #define PG8_STAGE(bufoff, gbase, voff) do { _Pragma("unroll") for (int _i = 0; _i < 2; ++_i) \
;         __builtin_amdgcn_global_load_lds((const unsigned*)((const char*)(gbase) + (voff)[_i]), (PG8_LAS unsigned*)(lds + (bufoff) + ldsw + _i * 8192), 16, 0, 0); } while (0)
; #define PG8_BAR __builtin_amdgcn_s_barrier()
; template <class Epi, class Sched, bool ALIGN_EPI = false, bool SP2 = false>
; __device__ __forceinline__ void gemm_phase(PG8_LAS unsigned char* lds, const Gemm g, const Sched& S, const Epi& E) {
;     ...
;     for (int i = 0; i < 2; ++i) { int R, C; stage_rc(tid * 16 + i * 8192, R, C); const int Rb = Epi::PERM ? (64 * (R >> 5) + perm32(R & 31)) : R;
;         voffA[i] = (unsigned)(R * K + C) * 2u; voffB[i] = (unsigned)(Rb * K + C) * 2u; }
;     ...
;         PG8_STAGE(PG8_SB(0, 0), cB, voffB); PG8_STAGE(PG8_SB(0, 1), cB + hstepB, voffB); PG8_STAGE(PG8_SA(0, 0), cA, voffA); PG8_STAGE(PG8_SA(0, 1), cA + hstep, voffA);
;         if (wr == 1) PG8_BAR;
.LBB0_917:
	s_andn2_b64 vcc, exec, s[26:27]
	s_cbranch_vccnz .LBB0_1052
	v_readlane_b32 s0, v252, 59
	s_waitcnt vmcnt(0) lgkmcnt(0)
	v_mov_b32_e32 v3, v0
	v_readlane_b32 s1, v252, 60
	s_mul_i32 s82, s22, 0x14000
	s_andn2_b64 vcc, exec, s[0:1]
	v_readfirstlane_b32 s36, v3
	s_cbranch_vccnz .LBB0_998
	v_lshlrev_b32_e32 v1, 4, v3
	v_add_u32_e32 v4, 0x2000, v1
	v_ashrrev_i32_e32 v2, 31, v4
	v_lshrrev_b32_e32 v2, 22, v2
	v_add_u32_e32 v2, v4, v2
	v_ashrrev_i32_e32 v2, 10, v2
	v_mul_i32_i24_e32 v5, 0x400, v2
	v_sub_u32_e32 v4, v4, v5
	v_lshrrev_b32_e32 v5, 4, v4
	v_bitop3_b32 v5, v5, v4, 32 bitop3:0x6c
	v_ashrrev_i32_e32 v4, 31, v5
	v_lshrrev_b32_e32 v4, 26, v4
	v_add_u32_e32 v6, v5, v4
	v_lshlrev_b32_e32 v8, 3, v2
	v_ashrrev_i32_e32 v4, 6, v6
	v_and_b32_e32 v8, -16, v8
	v_add_u32_e32 v8, v4, v8
	v_lshrrev_b32_e32 v9, 2, v8
	v_lshlrev_b32_e32 v10, 1, v8
	v_and_b32_e32 v6, 0xc0, v6
	v_and_b32_e32 v7, 3, v4
	v_and_b32_e32 v9, 4, v9
	v_and_b32_e32 v10, 0xfffd8, v10
	v_sub_u32_e32 v5, v5, v6
	v_or3_b32 v7, v7, v9, v10
	v_lshlrev_b32_e32 v9, 5, v2
	v_ashrrev_i16_sdwa v5, v225, sext(v5) dst_sel:DWORD dst_unused:UNUSED_PAD src0_sel:DWORD src1_sel:BYTE_0
	v_and_b32_e32 v9, 32, v9
	v_bfe_i32 v5, v5, 0, 16
	v_add_lshl_u32 v6, v9, v5, 1
	v_lshl_add_u32 v206, v7, 12, v6
	v_lshl_add_u32 v208, v8, 12, v6
	v_bfe_i32 v6, v3, 27, 1
	v_lshrrev_b32_e32 v6, 22, v6
	v_add_u32_e32 v6, v1, v6
	v_and_b32_e32 v6, 0xfffffc00, v6
	v_sub_u32_e32 v1, v1, v6
	v_lshrrev_b32_e32 v6, 4, v1
	v_ashrrev_i32_e32 v7, 31, v3
	v_bitop3_b32 v1, v6, v1, 32 bitop3:0x6c
	v_lshrrev_b32_e32 v7, 26, v7
	v_ashrrev_i32_e32 v6, 31, v1
	v_add_u32_e32 v7, v3, v7
	v_lshrrev_b32_e32 v6, 26, v6
	v_ashrrev_i32_e32 v7, 6, v7
	v_add_u32_e32 v8, v1, v6
	v_lshlrev_b32_e32 v10, 3, v7
	v_ashrrev_i32_e32 v6, 6, v8
	v_and_b32_e32 v10, -16, v10
	v_add_u32_e32 v10, v6, v10
	v_lshrrev_b32_e32 v11, 2, v10
	v_lshlrev_b32_e32 v12, 1, v10
	v_and_b32_e32 v8, 0xc0, v8
	v_and_b32_e32 v9, 3, v6
	v_and_b32_e32 v11, 4, v11
	v_and_b32_e32 v12, 0xfffd8, v12
	v_sub_u32_e32 v1, v1, v8
	s_ashr_i32 s37, s36, 6
	v_or3_b32 v9, v9, v11, v12
	v_lshlrev_b32_e32 v11, 5, v7
	v_ashrrev_i16_sdwa v1, v225, sext(v1) dst_sel:DWORD dst_unused:UNUSED_PAD src0_sel:DWORD src1_sel:BYTE_0
	s_lshl_b32 s25, s37, 10
	v_and_b32_e32 v11, 32, v11
	v_bfe_i32 v8, v1, 0, 16
	v_add_lshl_u32 v1, v11, v8, 1
	s_add_i32 s66, s25, 0
	v_readlane_b32 s0, v254, 36
	v_lshl_add_u32 v190, v9, 12, v1
	s_add_i32 m0, s66, 0x10000
	v_readlane_b32 s1, v254, 37
	v_lshl_add_u32 v210, v10, 12, v1
	s_add_i32 s67, s66, 0x2000
	s_add_i32 s59, s66, 0x4000
	s_add_i32 s74, s66, 0x6000
	s_ashr_i32 s38, s36, 8
	global_load_lds_dwordx4 v190, s[0:1]
	s_add_i32 m0, s66, 0x12000
	s_mov_b32 s20, s22
	global_load_lds_dwordx4 v206, s[0:1]
	v_readlane_b32 s0, v254, 30
	s_add_i32 m0, s66, 0x14000
	v_readlane_b32 s1, v254, 31
	s_nop 4
	global_load_lds_dwordx4 v190, s[0:1]
	s_add_i32 m0, s66, 0x16000
	s_cmp_eq_u32 s38, 1
	global_load_lds_dwordx4 v206, s[0:1]
	v_readlane_b32 s0, v254, 32
	s_mov_b32 m0, s66
	v_readlane_b32 s1, v254, 33
	s_cselect_b64 s[26:27], -1, 0
	s_cmp_lg_u32 s38, 1
	s_nop 2
	global_load_lds_dwordx4 v210, s[0:1]
	s_mov_b32 m0, s67
	s_nop 0
	global_load_lds_dwordx4 v208, s[0:1]
	v_readlane_b32 s0, v254, 34
	s_mov_b32 m0, s59
	v_readlane_b32 s1, v254, 35
	s_nop 4
	global_load_lds_dwordx4 v210, s[0:1]
	s_mov_b32 m0, s74
	s_nop 0
	global_load_lds_dwordx4 v208, s[0:1]
	s_setprio 1
	s_cbranch_scc1 .LBB0_921
	s_barrier
	s_setprio 0

; #define PG8_STAGE(bufoff, gbase, voff) do { _Pragma("unroll") for (int _i = 0; _i < 2; ++_i) \
;         __builtin_amdgcn_global_load_lds((const unsigned*)((const char*)(gbase) + (voff)[_i]), (PG8_LAS unsigned*)(lds + (bufoff) + ldsw + _i * 8192), 16, 0, 0); } while (0)
; #define PG8_BAR __builtin_amdgcn_s_barrier()
; template <class Epi, class Sched, bool ALIGN_EPI = false, bool SP2 = false>
; __device__ __forceinline__ void gemm_phase(PG8_LAS unsigned char* lds, const Gemm g, const Sched& S, const Epi& E) {
;     ...
;     for (int i = 0; i < 2; ++i) { int R, C; stage_rc(tid * 16 + i * 8192, R, C); const int Rb = Epi::PERM ? (64 * (R >> 5) + perm32(R & 31)) : R;
;         voffA[i] = (unsigned)(R * K + C) * 2u; voffB[i] = (unsigned)(Rb * K + C) * 2u; }
;     ...
;         PG8_STAGE(PG8_SB(0, 0), cB, voffB); PG8_STAGE(PG8_SB(0, 1), cB + hstepB, voffB); PG8_STAGE(PG8_SA(0, 0), cA, voffA); PG8_STAGE(PG8_SA(0, 1), cA + hstep, voffA);
;         if (wr == 1) PG8_BAR;
.LBB0_1056:
	s_add_i32 s66, s25, s59
	v_readlane_b32 s4, v250, 10
	v_readlane_b32 s5, v250, 11
	s_cmp_le_i32 s4, s66
	s_cselect_b64 s[0:1], -1, 0
	s_cmp_lt_i32 s66, s5
	s_cselect_b64 s[4:5], -1, 0
	s_and_b64 s[0:1], s[0:1], s[4:5]
	s_andn2_b64 vcc, exec, s[0:1]
	s_cbranch_vccnz .LBB0_1055
	s_cmp_eq_u32 s59, 0
	s_cbranch_scc1 .LBB0_1173
	v_readlane_b32 s0, v252, 61
	v_mov_b32_e32 v6, v0
	v_readlane_b32 s1, v252, 62
	s_andn2_b64 vcc, exec, s[0:1]
	v_readfirstlane_b32 s4, v6
	s_cbranch_vccnz .LBB0_1175
	v_lshlrev_b32_e32 v1, 4, v6
	v_add_u32_e32 v2, 0x2000, v1
	s_waitcnt vmcnt(0) lgkmcnt(0)
	v_ashrrev_i32_e32 v3, 31, v2
	v_lshrrev_b32_e32 v3, 22, v3
	v_add_u32_e32 v3, v2, v3
	v_ashrrev_i32_e32 v7, 10, v3
	v_mul_i32_i24_e32 v3, 0x400, v7
	v_sub_u32_e32 v2, v2, v3
	v_lshrrev_b32_e32 v3, 4, v2
	v_bitop3_b32 v2, v3, v2, 32 bitop3:0x6c
	v_ashrrev_i32_e32 v3, 31, v2
	v_lshrrev_b32_e32 v3, 26, v3
	v_add_u32_e32 v3, v2, v3
	v_lshlrev_b32_e32 v5, 3, v7
	v_ashrrev_i32_e32 v8, 6, v3
	v_and_b32_e32 v5, -16, v5
	v_add_u32_e32 v5, v8, v5
	v_lshrrev_b32_e32 v9, 2, v5
	v_lshlrev_b32_e32 v10, 1, v5
	v_and_b32_e32 v3, 0xc0, v3
	v_and_b32_e32 v4, 3, v8
	v_and_b32_e32 v9, 4, v9
	v_and_b32_e32 v10, 0x3ffd8, v10
	v_sub_u32_e32 v2, v2, v3
	v_or3_b32 v4, v4, v9, v10
	v_lshlrev_b32_e32 v9, 5, v7
	v_ashrrev_i16_sdwa v2, v225, sext(v2) dst_sel:DWORD dst_unused:UNUSED_PAD src0_sel:DWORD src1_sel:BYTE_0
	v_and_b32_e32 v10, 32, v9
	v_bfe_i32 v9, v2, 0, 16
	v_add_lshl_u32 v2, v10, v9, 1
	v_lshl_add_u32 v142, v4, 14, v2
	v_lshl_add_u32 v144, v5, 14, v2
	v_bfe_i32 v2, v6, 27, 1
	v_lshrrev_b32_e32 v2, 22, v2
	v_add_u32_e32 v2, v1, v2
	v_and_b32_e32 v2, 0xfffffc00, v2
	v_sub_u32_e32 v1, v1, v2
	v_lshrrev_b32_e32 v2, 4, v1
	v_ashrrev_i32_e32 v4, 31, v6
	v_bitop3_b32 v1, v2, v1, 32 bitop3:0x6c
	v_lshrrev_b32_e32 v4, 26, v4
	v_ashrrev_i32_e32 v2, 31, v1
	v_add_u32_e32 v4, v6, v4
	v_lshrrev_b32_e32 v2, 26, v2
	v_ashrrev_i32_e32 v11, 6, v4
	v_add_u32_e32 v2, v1, v2
	v_lshlrev_b32_e32 v4, 3, v11
	s_add_i32 s82, s59, -1
	v_ashrrev_i32_e32 v10, 6, v2
	v_and_b32_e32 v4, -16, v4
	s_lshl_b32 s0, s82, 27
	v_add_u32_e32 v4, v10, v4
	s_and_b32 s0, s0, 0x8000000
	v_lshrrev_b32_e32 v5, 2, v4
	v_lshlrev_b32_e32 v12, 1, v4
	v_and_b32_e32 v2, 0xc0, v2
	s_add_u32 s0, s64, s0
	v_and_b32_e32 v3, 3, v10
	v_and_b32_e32 v5, 4, v5
	v_and_b32_e32 v12, 0x3ffd8, v12
	v_sub_u32_e32 v1, v1, v2
	s_addc_u32 s1, s65, 0
	s_ashr_i32 s6, s4, 6
	v_or3_b32 v3, v3, v5, v12
	v_lshlrev_b32_e32 v5, 5, v11
	v_ashrrev_i16_sdwa v1, v225, sext(v1) dst_sel:DWORD dst_unused:UNUSED_PAD src0_sel:DWORD src1_sel:BYTE_0
	s_lshl_b32 s67, s6, 10
	v_and_b32_e32 v5, 32, v5
	v_bfe_i32 v12, v1, 0, 16
	v_add_lshl_u32 v1, v5, v12, 1
	s_add_i32 s74, s67, 0
	v_readlane_b32 s8, v249, 13
	v_lshl_add_u32 v146, v3, 14, v1
	s_add_i32 m0, s74, 0x10000
	v_readlane_b32 s9, v249, 14
	s_ashr_i32 s5, s4, 8
	v_lshl_add_u32 v190, v4, 14, v1
	v_mov_b32_e32 v145, v191
	s_nop 1
	global_load_lds_dwordx4 v146, s[8:9]
	s_add_i32 m0, s74, 0x12000
	s_nop 0
	global_load_lds_dwordx4 v142, s[8:9]
	v_readlane_b32 s8, v249, 26
	s_add_i32 m0, s74, 0x14000
	v_readlane_b32 s9, v249, 27
	s_nop 4
	global_load_lds_dwordx4 v146, s[8:9]
	s_add_i32 m0, s74, 0x16000
	s_nop 0
	global_load_lds_dwordx4 v142, s[8:9]
	v_readlane_b32 s8, v249, 24
	v_readlane_b32 s9, v249, 25
	s_add_u32 s38, s0, s8
	s_addc_u32 s39, s1, s9
	s_add_i32 s75, s74, 0x2000
	s_mov_b32 m0, s74
	s_add_u32 s8, s38, 0x200000
	global_load_lds_dwordx4 v190, s[38:39]
	s_mov_b32 m0, s75
	s_addc_u32 s9, s39, 0
	s_add_i32 s86, s74, 0x4000
	global_load_lds_dwordx4 v144, s[38:39]
	s_mov_b32 m0, s86
	s_add_i32 s87, s74, 0x6000
	global_load_lds_dwordx4 v190, s[8:9]
	s_mov_b32 m0, s87
	s_cmp_eq_u32 s5, 1
	global_load_lds_dwordx4 v144, s[8:9]
	v_lshl_add_u64 v[2:3], s[38:39], 0, v[190:191]
	s_cselect_b64 s[54:55], -1, 0
	s_cmp_lg_u32 s5, 1
	v_lshl_add_u64 v[4:5], s[38:39], 0, v[144:145]
	s_setprio 1
	s_cbranch_scc1 .LBB0_1061
	s_barrier
	s_setprio 0

; #define PG8_STAGE(bufoff, gbase, voff) do { _Pragma("unroll") for (int _i = 0; _i < 2; ++_i) \
;         __builtin_amdgcn_global_load_lds((const unsigned*)((const char*)(gbase) + (voff)[_i]), (PG8_LAS unsigned*)(lds + (bufoff) + ldsw + _i * 8192), 16, 0, 0); } while (0)
; #define PG8_BAR __builtin_amdgcn_s_barrier()
; template <class Epi, class Sched, bool ALIGN_EPI = false, bool SP2 = false>
; __device__ __forceinline__ void gemm_phase(PG8_LAS unsigned char* lds, const Gemm g, const Sched& S, const Epi& E) {
;     ...
;     for (int i = 0; i < 2; ++i) { int R, C; stage_rc(tid * 16 + i * 8192, R, C); const int Rb = Epi::PERM ? (64 * (R >> 5) + perm32(R & 31)) : R;
;         voffA[i] = (unsigned)(R * K + C) * 2u; voffB[i] = (unsigned)(Rb * K + C) * 2u; }
;     ...
;         PG8_STAGE(PG8_SB(0, 0), cB, voffB); PG8_STAGE(PG8_SB(0, 1), cB + hstepB, voffB); PG8_STAGE(PG8_SA(0, 0), cA, voffA); PG8_STAGE(PG8_SA(0, 1), cA + hstep, voffA);
;         if (wr == 1) PG8_BAR;
.LBB0_1222:
	s_or_b64 exec, exec, s[26:27]
	s_waitcnt vmcnt(0)
	v_ashrrev_i32_e32 v2, 31, v26
	v_lshrrev_b32_e32 v2, 26, v2
	v_add_u32_e32 v2, v26, v2
	v_ashrrev_i32_e32 v6, 6, v2
	v_bfe_i32 v2, v26, 27, 1
	v_lshlrev_b32_e32 v1, 4, v26
	v_lshrrev_b32_e32 v2, 22, v2
	v_add_u32_e32 v2, v1, v2
	v_and_b32_e32 v2, 0xfffffc00, v2
	v_sub_u32_e32 v2, v1, v2
	v_lshrrev_b32_e32 v3, 4, v2
	v_bitop3_b32 v2, v3, v2, 32 bitop3:0x6c
	v_ashrrev_i32_e32 v4, 31, v2
	v_lshrrev_b32_e32 v4, 26, v4
	v_add_u32_e32 v4, v2, v4
	v_lshlrev_b32_e32 v3, 3, v6
	v_ashrrev_i32_e32 v7, 6, v4
	v_and_b32_e32 v4, 0xc0, v4
	v_and_b32_e32 v3, -16, v3
	v_sub_u32_e32 v2, v2, v4
	v_add_u32_e32 v3, v7, v3
	v_ashrrev_i16_sdwa v2, v225, sext(v2) dst_sel:DWORD dst_unused:UNUSED_PAD src0_sel:DWORD src1_sel:BYTE_0
	v_lshlrev_b32_e32 v5, 5, v6
	v_bfe_i32 v8, v2, 0, 16
	v_lshlrev_b32_e32 v2, 1, v3
	v_lshrrev_b32_e32 v4, 2, v3
	v_and_b32_e32 v5, 32, v5
	v_and_b32_e32 v4, 4, v4
	v_and_b32_e32 v9, 3, v7
	v_and_b32_e32 v2, 0xfffd8, v2
	v_or3_b32 v2, v9, v4, v2
	v_add_lshl_u32 v4, v5, v8, 1
	v_add_u32_e32 v1, 0x2000, v1
	v_lshl_add_u32 v130, v2, 12, v4
	v_ashrrev_i32_e32 v2, 31, v1
	v_lshrrev_b32_e32 v2, 22, v2
	v_add_u32_e32 v2, v1, v2
	v_ashrrev_i32_e32 v9, 10, v2
	v_mul_i32_i24_e32 v2, 0x400, v9
	v_sub_u32_e32 v1, v1, v2
	v_lshrrev_b32_e32 v2, 4, v1
	v_bitop3_b32 v1, v2, v1, 32 bitop3:0x6c
	v_lshl_add_u32 v190, v3, 12, v4
	v_ashrrev_i32_e32 v3, 31, v1
	v_lshrrev_b32_e32 v3, 26, v3
	v_add_u32_e32 v3, v1, v3
	s_lshl_b64 s[0:1], s[82:83], 12
	v_lshlrev_b32_e32 v2, 3, v9
	v_ashrrev_i32_e32 v10, 6, v3
	v_and_b32_e32 v3, 0xc0, v3
	s_add_u32 s0, s52, s0
	v_and_b32_e32 v2, -16, v2
	v_sub_u32_e32 v1, v1, v3
	s_addc_u32 s1, s53, s1
	s_ashr_i32 s4, s36, 6
	v_add_u32_e32 v2, v10, v2
	v_ashrrev_i16_sdwa v1, v225, sext(v1) dst_sel:DWORD dst_unused:UNUSED_PAD src0_sel:DWORD src1_sel:BYTE_0
	v_lshlrev_b32_e32 v4, 5, v9
	v_bfe_i32 v11, v1, 0, 16
	v_lshlrev_b32_e32 v1, 1, v2
	v_lshrrev_b32_e32 v3, 2, v2
	s_lshl_b32 s42, s4, 10
	v_and_b32_e32 v4, 32, v4
	v_and_b32_e32 v3, 4, v3
	v_and_b32_e32 v5, 3, v10
	v_and_b32_e32 v1, 0xfffd8, v1
	s_add_i32 s51, s42, 0
	v_readlane_b32 s6, v252, 17
	v_or3_b32 v1, v5, v3, v1
	v_add_lshl_u32 v3, v4, v11, 1
	s_add_i32 m0, s51, 0x10000
	v_readlane_b32 s7, v252, 18
	v_lshl_add_u32 v134, v1, 12, v3
	s_ashr_i32 s5, s36, 8
	v_lshl_add_u32 v132, v2, 12, v3
	v_mov_b32_e32 v133, v191
	s_nop 0
	global_load_lds_dwordx4 v130, s[6:7]
	s_add_i32 m0, s51, 0x12000
	s_nop 0
	global_load_lds_dwordx4 v134, s[6:7]
	v_readlane_b32 s6, v249, 11
	s_add_i32 m0, s51, 0x14000
	v_readlane_b32 s7, v249, 12
	s_nop 4
	global_load_lds_dwordx4 v130, s[6:7]
	s_add_i32 m0, s51, 0x16000
	s_nop 0
	global_load_lds_dwordx4 v134, s[6:7]
	v_readlane_b32 s6, v249, 31
	v_readlane_b32 s7, v249, 32
	s_add_u32 s68, s0, s6
	s_addc_u32 s69, s1, s7
	s_add_i32 s67, s51, 0x2000
	s_mov_b32 m0, s51
	s_add_u32 s6, s68, 0x80000
	global_load_lds_dwordx4 v190, s[68:69]
	s_mov_b32 m0, s67
	s_addc_u32 s7, s69, 0
	s_add_i32 s74, s51, 0x4000
	global_load_lds_dwordx4 v132, s[68:69]
	s_mov_b32 m0, s74
	s_add_i32 s75, s51, 0x6000
	global_load_lds_dwordx4 v190, s[6:7]
	s_mov_b32 m0, s75
	s_cmp_eq_u32 s5, 1
	global_load_lds_dwordx4 v132, s[6:7]
	v_lshl_add_u64 v[2:3], s[68:69], 0, v[190:191]
	s_cselect_b64 s[26:27], -1, 0
	s_cmp_lg_u32 s5, 1
	v_lshl_add_u64 v[4:5], s[68:69], 0, v[132:133]
	s_setprio 1
	s_cbranch_scc1 .LBB0_1224
	s_barrier
	s_setprio 0
